# attention: P.V computed transposed so a lane owns one query row; rescale by the lane's own alpha without LDS; epilogue 8 x 16-byte stores per lane instead of 64 two-byte stores
# baseline (speedup 1.0000x reference)
; __device__ __forceinline__ u16 f2bf(float x) { return (u16)(cvtpk(x, 0.f) & 0xffffu); }
; __device__ __forceinline__ int crow(int r, int hi) { return (r & 3) + 8 * (r >> 2) + 4 * hi; }
; __device__ __forceinline__ void attn_dense_body(const u16* __restrict__ Qb, const u16* __restrict__ Kh, const u16* __restrict__ Vh,
;                                                 u16* __restrict__ Ob, int seq, char* lds, int tid) {
;     ...
;   if (hi == 0) li_l[r32] = l_reg; asm volatile("s_waitcnt lgkmcnt(0)" ::: "memory");
;   float rli[16];
; #pragma unroll
;   for (int r = 0; r < 16; ++r) rli[r] = __builtin_amdgcn_rcpf(li_l[crow(r, hi)]);
;   u16* Ow = Ob + (long)(wid * 32) * AT_LDO;
; #pragma unroll
;   for (int r = 0; r < 16; ++r) { int orow = crow(r, hi);
; #pragma unroll
;     for (int d0 = 0; d0 < 4; ++d0) Ow[(long)orow * AT_LDO + d0 * 32 + r32] = f2bf(o[d0][r] * rli[r]); }
.LBB0_184:
	v_rcp_f32_e32 v73, v64
	s_lshl_b64 s[0:1], s[6:7], 11
	s_add_u32 s0, s2, s0
	s_addc_u32 s1, s3, s1
	s_lshl_b32 s4, s55, 1
	s_add_u32 s0, s0, s4
	s_addc_u32 s1, s1, 0
	v_lshrrev_b32_e32 v65, 6, v203
	v_and_b32_e32 v66, 31, v203
	v_lshl_or_b32 v65, v65, 5, v66
	v_bfe_u32 v66, v203, 5, 1
	v_lshlrev_b32_e32 v66, 4, v66
	v_lshl_add_u32 v65, v65, 11, v66
	v_mul_f32_e32 v0, v0, v73
	v_mul_f32_e32 v1, v1, v73
	v_mul_f32_e32 v2, v2, v73
	v_mul_f32_e32 v3, v3, v73
	v_mul_f32_e32 v4, v4, v73
	v_mul_f32_e32 v5, v5, v73
	v_mul_f32_e32 v6, v6, v73
	v_mul_f32_e32 v7, v7, v73
	v_mul_f32_e32 v8, v8, v73
	v_mul_f32_e32 v9, v9, v73
	v_mul_f32_e32 v10, v10, v73
	v_mul_f32_e32 v11, v11, v73
	v_mul_f32_e32 v12, v12, v73
	v_mul_f32_e32 v13, v13, v73
	v_mul_f32_e32 v14, v14, v73
	v_mul_f32_e32 v15, v15, v73
	v_cvt_pk_bf16_f32 v76, v0, v1
	v_cvt_pk_bf16_f32 v77, v2, v3
	v_cvt_pk_bf16_f32 v78, v4, v5
	v_cvt_pk_bf16_f32 v79, v6, v7
	v_cvt_pk_bf16_f32 v80, v8, v9
	v_cvt_pk_bf16_f32 v81, v10, v11
	v_cvt_pk_bf16_f32 v82, v12, v13
	v_cvt_pk_bf16_f32 v83, v14, v15
	s_nop 1
	v_permlane32_swap_b32_e32 v76, v78
	v_permlane32_swap_b32_e32 v77, v79
	v_permlane32_swap_b32_e32 v80, v82
	v_permlane32_swap_b32_e32 v81, v83
	global_store_dwordx4 v65, v[76:79], s[0:1] offset:0
	global_store_dwordx4 v65, v[80:83], s[0:1] offset:32
	v_mul_f32_e32 v48, v48, v73
	v_mul_f32_e32 v49, v49, v73
	v_mul_f32_e32 v50, v50, v73
	v_mul_f32_e32 v51, v51, v73
	v_mul_f32_e32 v52, v52, v73
	v_mul_f32_e32 v53, v53, v73
	v_mul_f32_e32 v54, v54, v73
	v_mul_f32_e32 v55, v55, v73
	v_mul_f32_e32 v56, v56, v73
	v_mul_f32_e32 v57, v57, v73
	v_mul_f32_e32 v58, v58, v73
	v_mul_f32_e32 v59, v59, v73
	v_mul_f32_e32 v60, v60, v73
	v_mul_f32_e32 v61, v61, v73
	v_mul_f32_e32 v62, v62, v73
	v_mul_f32_e32 v63, v63, v73
	v_cvt_pk_bf16_f32 v84, v48, v49
	v_cvt_pk_bf16_f32 v85, v50, v51
	v_cvt_pk_bf16_f32 v86, v52, v53
	v_cvt_pk_bf16_f32 v87, v54, v55
	v_cvt_pk_bf16_f32 v88, v56, v57
	v_cvt_pk_bf16_f32 v89, v58, v59
	v_cvt_pk_bf16_f32 v90, v60, v61
	v_cvt_pk_bf16_f32 v91, v62, v63
	s_nop 1
	v_permlane32_swap_b32_e32 v84, v86
	v_permlane32_swap_b32_e32 v85, v87
	v_permlane32_swap_b32_e32 v88, v90
	v_permlane32_swap_b32_e32 v89, v91
	global_store_dwordx4 v65, v[84:87], s[0:1] offset:64
	global_store_dwordx4 v65, v[88:91], s[0:1] offset:96
	v_mul_f32_e32 v32, v32, v73
	v_mul_f32_e32 v33, v33, v73
	v_mul_f32_e32 v34, v34, v73
	v_mul_f32_e32 v35, v35, v73
	v_mul_f32_e32 v36, v36, v73
	v_mul_f32_e32 v37, v37, v73
	v_mul_f32_e32 v38, v38, v73
	v_mul_f32_e32 v39, v39, v73
	v_mul_f32_e32 v40, v40, v73
	v_mul_f32_e32 v41, v41, v73
	v_mul_f32_e32 v42, v42, v73
	v_mul_f32_e32 v43, v43, v73
	v_mul_f32_e32 v44, v44, v73
	v_mul_f32_e32 v45, v45, v73
	v_mul_f32_e32 v46, v46, v73
	v_mul_f32_e32 v47, v47, v73
	v_cvt_pk_bf16_f32 v76, v32, v33
	v_cvt_pk_bf16_f32 v77, v34, v35
	v_cvt_pk_bf16_f32 v78, v36, v37
	v_cvt_pk_bf16_f32 v79, v38, v39
	v_cvt_pk_bf16_f32 v80, v40, v41
	v_cvt_pk_bf16_f32 v81, v42, v43
	v_cvt_pk_bf16_f32 v82, v44, v45
	v_cvt_pk_bf16_f32 v83, v46, v47
	s_nop 1
	v_permlane32_swap_b32_e32 v76, v78
	v_permlane32_swap_b32_e32 v77, v79
	v_permlane32_swap_b32_e32 v80, v82
	v_permlane32_swap_b32_e32 v81, v83
	global_store_dwordx4 v65, v[76:79], s[0:1] offset:128
	global_store_dwordx4 v65, v[80:83], s[0:1] offset:160
	v_mul_f32_e32 v16, v16, v73
	v_mul_f32_e32 v17, v17, v73
	v_mul_f32_e32 v18, v18, v73
	v_mul_f32_e32 v19, v19, v73
	v_mul_f32_e32 v20, v20, v73
	v_mul_f32_e32 v21, v21, v73
	v_mul_f32_e32 v22, v22, v73
	v_mul_f32_e32 v23, v23, v73
	v_mul_f32_e32 v24, v24, v73
	v_mul_f32_e32 v25, v25, v73
	v_mul_f32_e32 v26, v26, v73
	v_mul_f32_e32 v27, v27, v73
	v_mul_f32_e32 v28, v28, v73
	v_mul_f32_e32 v29, v29, v73
	v_mul_f32_e32 v30, v30, v73
	v_mul_f32_e32 v31, v31, v73
	v_cvt_pk_bf16_f32 v84, v16, v17
	v_cvt_pk_bf16_f32 v85, v18, v19
	v_cvt_pk_bf16_f32 v86, v20, v21
	v_cvt_pk_bf16_f32 v87, v22, v23
	v_cvt_pk_bf16_f32 v88, v24, v25
	v_cvt_pk_bf16_f32 v89, v26, v27
	v_cvt_pk_bf16_f32 v90, v28, v29
	v_cvt_pk_bf16_f32 v91, v30, v31
	s_nop 1
	v_permlane32_swap_b32_e32 v84, v86
	v_permlane32_swap_b32_e32 v85, v87
	v_permlane32_swap_b32_e32 v88, v90
	v_permlane32_swap_b32_e32 v89, v91
	global_store_dwordx4 v65, v[84:87], s[0:1] offset:192
	global_store_dwordx4 v65, v[88:91], s[0:1] offset:224
	s_add_i32 s54, s54, s71
	s_cmp_ge_i32 s54, s53
	s_barrier
	s_cbranch_scc1 .LBB0_178

; __device__ __forceinline__ void finishSM(f32x16& p0, f32x16& p1, float alpha, float& l_reg, bf16x8& pa0, bf16x8& pa1, bf16x8& pa2, bf16x8& pa3) {
; #pragma unroll
;   for (int r = 0; r < 16; ++r) p1[r] = __builtin_amdgcn_exp2f(p1[r]);
;   float ps = 0;
; #pragma unroll
;   for (int r = 0; r < 16; ++r) ps += p0[r];
; #pragma unroll
;   for (int r = 0; r < 16; ++r) ps += p1[r];
;   { auto rr = __builtin_amdgcn_permlane32_swap(__float_as_uint(ps), __float_as_uint(ps), false, false);
;     ps = __uint_as_float(rr[0]) + __uint_as_float(rr[1]); }
;   l_reg = l_reg * alpha + ps;
;     ...
;   PK4(p0, 0, pa0); PK4(p0, 8, pa1); PK4(p1, 0, pa2); PK4(p1, 8, pa3);
;     ...
; }
; __device__ __forceinline__ void qkt(f32x16& p0, f32x16& p1, const char* Ks, const bf16x8* qr, int r32, int hi) {
; #pragma unroll
;   for (int r = 0; r < 16; ++r) { p0[r] = 0.f; p1[r] = 0.f; }
; #pragma unroll
;   for (int d0 = 0; d0 < 8; ++d0) { int cb = (d0 * 16 + hi * 8) * 2;
;     bf16x8 b0 = *reinterpret_cast<const bf16x8*>(Ks + KSWZ(r32, cb));
;     bf16x8 b1 = *reinterpret_cast<const bf16x8*>(Ks + KSWZ(32 + r32, cb));
;     p0 = __builtin_amdgcn_mfma_f32_32x32x16_bf16(b0, qr[d0], p0, 0, 0, 0);
;     p1 = __builtin_amdgcn_mfma_f32_32x32x16_bf16(b1, qr[d0], p1, 0, 0, 0); }
; }
.LBB0_190:
	ds_read_b128 v[64:67], v191 offset:49152
	ds_read_b128 v[68:71], v191 offset:57344
	ds_read_b128 v[216:219], v196 offset:49152
	ds_read_b128 v[220:223], v196 offset:57344
	v_add_f32_e32 v160, 0, v161
	v_add_f32_e32 v160, v175, v160
	s_waitcnt lgkmcnt(3)
	v_mfma_f32_32x32x16_bf16 v[80:95], v[64:67], v[116:119], 0
	v_add_f32_e32 v160, v162, v160
	v_add_f32_e32 v160, v212, v160
	v_add_f32_e32 v160, v174, v160
	v_add_f32_e32 v160, v215, v160
	v_add_f32_e32 v160, v163, v160
	v_add_f32_e32 v160, v173, v160
	v_add_f32_e32 v160, v164, v160
	s_waitcnt lgkmcnt(2)
	v_mfma_f32_32x32x16_bf16 v[64:79], v[68:71], v[116:119], 0
	v_add_f32_e32 v160, v171, v160
	v_add_f32_e32 v160, v165, v160
	v_add_f32_e32 v160, v172, v160
	v_exp_f32_e32 v158, v158
	v_add_f32_e32 v160, v166, v160
	v_exp_f32_e32 v159, v159
	v_add_f32_e32 v160, v169, v160
	s_waitcnt lgkmcnt(1)
	v_mfma_f32_32x32x16_bf16 v[80:95], v[216:219], v[108:111], v[80:95]
	v_exp_f32_e32 v156, v156
	v_add_f32_e32 v160, v167, v160
	v_exp_f32_e32 v157, v157
	v_add_f32_e32 v160, v170, v160
	v_exp_f32_e32 v152, v152
	v_add_f32_e32 v160, v158, v160
	v_exp_f32_e32 v153, v153
	s_waitcnt lgkmcnt(0)
	v_mfma_f32_32x32x16_bf16 v[64:79], v[220:223], v[108:111], v[64:79]
	ds_read_b128 v[216:219], v195 offset:49152
	ds_read_b128 v[220:223], v195 offset:57344
	v_add_f32_e32 v160, v159, v160
	v_exp_f32_e32 v148, v148
	v_add_f32_e32 v160, v156, v160
	v_exp_f32_e32 v149, v149
	v_add_f32_e32 v160, v157, v160
	v_exp_f32_e32 v146, v146
	s_waitcnt lgkmcnt(1)
	v_mfma_f32_32x32x16_bf16 v[80:95], v[216:219], v[124:127], v[80:95]
	v_add_f32_e32 v160, v152, v160
	v_exp_f32_e32 v147, v147
	v_add_f32_e32 v160, v153, v160
	v_exp_f32_e32 v154, v154
	v_add_f32_e32 v160, v148, v160
	v_exp_f32_e32 v155, v155
	v_add_f32_e32 v160, v149, v160
	s_waitcnt lgkmcnt(0)
	v_mfma_f32_32x32x16_bf16 v[64:79], v[220:223], v[124:127], v[64:79]
	ds_read_b128 v[216:219], v194 offset:49152
	ds_read_b128 v[220:223], v194 offset:57344
	v_exp_f32_e32 v150, v150
	v_add_f32_e32 v160, v146, v160
	v_exp_f32_e32 v151, v151
	v_add_f32_e32 v160, v147, v160
	v_exp_f32_e32 v144, v144
	v_add_f32_e32 v160, v154, v160
	s_waitcnt lgkmcnt(1)
	v_mfma_f32_32x32x16_bf16 v[80:95], v[216:219], v[120:123], v[80:95]
	v_exp_f32_e32 v145, v145
	v_add_f32_e32 v160, v155, v160
	v_add_f32_e32 v160, v150, v160
	v_add_f32_e32 v160, v151, v160
	v_add_f32_e32 v160, v144, v160
	v_add_f32_e32 v209, v145, v160
	v_mov_b32_e32 v210, v209
	s_waitcnt lgkmcnt(0)
	v_mfma_f32_32x32x16_bf16 v[64:79], v[220:223], v[120:123], v[64:79]
	ds_read_b128 v[216:219], v193 offset:49152
	ds_read_b128 v[220:223], v193 offset:57344
	v_permlane32_swap_b32_e32 v209, v210
	s_waitcnt lgkmcnt(1)
	v_mfma_f32_32x32x16_bf16 v[80:95], v[216:219], v[112:115], v[80:95]
	s_waitcnt lgkmcnt(0)
	v_mfma_f32_32x32x16_bf16 v[64:79], v[220:223], v[112:115], v[64:79]
	ds_read_b128 v[216:219], v192 offset:49152
	ds_read_b128 v[220:223], v192 offset:57344
	s_waitcnt lgkmcnt(1)
	v_mfma_f32_32x32x16_bf16 v[80:95], v[216:219], v[104:107], v[80:95]
	s_waitcnt lgkmcnt(0)
	v_mfma_f32_32x32x16_bf16 v[64:79], v[220:223], v[104:107], v[64:79]
	ds_read_b128 v[216:219], v198 offset:49152
	ds_read_b128 v[220:223], v198 offset:57344
	s_waitcnt lgkmcnt(1)
	v_mfma_f32_32x32x16_bf16 v[80:95], v[216:219], v[100:103], v[80:95]
	s_waitcnt lgkmcnt(0)
	v_mfma_f32_32x32x16_bf16 v[64:79], v[220:223], v[100:103], v[64:79]
	ds_read_b128 v[216:219], v197 offset:49152
	ds_read_b128 v[220:223], v197 offset:57344
	v_cvt_pk_bf16_f32 v160, v161, v175
	v_cvt_pk_bf16_f32 v161, v162, v212
	v_cvt_pk_bf16_f32 v162, v174, v215
	v_cvt_pk_bf16_f32 v163, v163, v173
	v_cvt_pk_bf16_f32 v164, v164, v171
	v_cvt_pk_bf16_f32 v165, v165, v172
	s_waitcnt lgkmcnt(1)
	v_mfma_f32_32x32x16_bf16 v[80:95], v[216:219], v[96:99], v[80:95]
	v_permlane32_swap_b32_e32 v160, v162
	v_cvt_pk_bf16_f32 v166, v166, v169
	v_cvt_pk_bf16_f32 v167, v167, v170
	v_cvt_pk_bf16_f32 v170, v158, v159
	v_cvt_pk_bf16_f32 v171, v156, v157
	v_cvt_pk_bf16_f32 v172, v152, v153
	s_waitcnt lgkmcnt(0)
	v_mfma_f32_32x32x16_bf16 v[64:79], v[220:223], v[96:99], v[64:79]
	v_cvt_pk_bf16_f32 v173, v148, v149
	v_cvt_pk_bf16_f32 v212, v146, v147
	v_cvt_pk_bf16_f32 v213, v154, v155
	v_cvt_pk_bf16_f32 v214, v150, v151
	v_cvt_pk_bf16_f32 v215, v144, v145
	v_permlane32_swap_b32_e32 v161, v163
	v_permlane32_swap_b32_e32 v164, v166
	v_permlane32_swap_b32_e32 v165, v167
	v_permlane32_swap_b32_e32 v170, v172
	v_permlane32_swap_b32_e32 v171, v173
	v_permlane32_swap_b32_e32 v212, v214
	v_permlane32_swap_b32_e32 v213, v215
	s_movk_i32 s0, 0xa000
	v_add_co_u32_e32 v144, vcc, s0, v178
	s_movk_i32 s0, 0xc000
	s_nop 0
	v_addc_co_u32_e32 v145, vcc, -1, v179, vcc
	v_add_co_u32_e32 v148, vcc, s0, v178
	s_mov_b32 s0, 0xfeefa000
	s_nop 0
	v_addc_co_u32_e32 v149, vcc, -1, v179, vcc
	v_add_co_u32_e32 v152, vcc, s0, v178
	s_mov_b32 s0, 0xfeefc000
	s_nop 0
	v_addc_co_u32_e32 v153, vcc, -1, v179, vcc
	v_add_co_u32_e32 v156, vcc, s0, v178
	global_load_dwordx4 v[144:147], v[144:145], off
	s_nop 0
	global_load_dwordx4 v[148:151], v[148:149], off
	v_addc_co_u32_e32 v157, vcc, -1, v179, vcc
	global_load_dwordx4 v[152:155], v[152:153], off
	s_nop 0
	global_load_dwordx4 v[156:159], v[156:157], off
	ds_read_b64_tr_b16 v[216:217], v186 offset:0
	ds_read_b64_tr_b16 v[218:219], v186 offset:0x800
	ds_read_b64_tr_b16 v[220:221], v186 offset:0x1000
	ds_read_b64_tr_b16 v[222:223], v186 offset:0x1800
	ds_read_b64_tr_b16 v[224:225], v186 offset:0x2000
	ds_read_b64_tr_b16 v[226:227], v186 offset:0x2800
	ds_read_b64_tr_b16 v[228:229], v186 offset:0x3000
	ds_read_b64_tr_b16 v[230:231], v186 offset:0x3800
	s_waitcnt lgkmcnt(0)
; #define SBAR() __builtin_amdgcn_sched_barrier(0)
; template <int D0> __device__ __forceinline__ void pv_one(f32x16& od, int vb, bf16x8 pa0, bf16x8 pa1, bf16x8 pa2, bf16x8 pa3) {
;   const s16x4 l0 = tr_read<v_rd_off(D0, 0, 0)>(vb), h0 = tr_read<v_rd_off(D0, 0, 1)>(vb), l1 = tr_read<v_rd_off(D0, 1, 0)>(vb), h1 = tr_read<v_rd_off(D0, 1, 1)>(vb);
;   const s16x4 l2 = tr_read<v_rd_off(D0, 2, 0)>(vb), h2 = tr_read<v_rd_off(D0, 2, 1)>(vb), l3 = tr_read<v_rd_off(D0, 3, 0)>(vb), h3 = tr_read<v_rd_off(D0, 3, 1)>(vb);
;   asm volatile("s_waitcnt lgkmcnt(0)" ::: "memory"); SBAR();
;     ...
;   od = __builtin_amdgcn_mfma_f32_32x32x16_bf16(pa0, PK(l0, h0), od, 0, 0, 0);
;   od = __builtin_amdgcn_mfma_f32_32x32x16_bf16(pa1, PK(l1, h1), od, 0, 0, 0);
;   od = __builtin_amdgcn_mfma_f32_32x32x16_bf16(pa2, PK(l2, h2), od, 0, 0, 0);
;   od = __builtin_amdgcn_mfma_f32_32x32x16_bf16(pa3, PK(l3, h3), od, 0, 0, 0);
;     ...
; }
; __device__ __forceinline__ void pv_d0(f32x16* o, int vb, bf16x8 pa0, bf16x8 pa1, bf16x8 pa2, bf16x8 pa3) {
;   pv_one<0>(o[0], vb, pa0, pa1, pa2, pa3); pv_one<1>(o[1], vb, pa0, pa1, pa2, pa3); pv_one<2>(o[2], vb, pa0, pa1, pa2, pa3); pv_one<3>(o[3], vb, pa0, pa1, pa2, pa3);
	s_nop 0
	v_mfma_f32_32x32x16_bf16 v[0:15], v[216:219], v[160:163], v[0:15]
	ds_read_b64_tr_b16 v[216:217], v186 offset:0x200
	ds_read_b64_tr_b16 v[218:219], v186 offset:0xa00
	v_mfma_f32_32x32x16_bf16 v[0:15], v[220:223], v[164:167], v[0:15]
	ds_read_b64_tr_b16 v[220:221], v186 offset:0x1200
	ds_read_b64_tr_b16 v[222:223], v186 offset:0x1a00
	v_mfma_f32_32x32x16_bf16 v[0:15], v[224:227], v[170:173], v[0:15]
	ds_read_b64_tr_b16 v[224:225], v186 offset:0x2200
	ds_read_b64_tr_b16 v[226:227], v186 offset:0x2a00
	v_mfma_f32_32x32x16_bf16 v[0:15], v[228:231], v[212:215], v[0:15]
	ds_read_b64_tr_b16 v[228:229], v186 offset:0x3200
	ds_read_b64_tr_b16 v[230:231], v186 offset:0x3a00
	s_waitcnt lgkmcnt(0)
	v_mfma_f32_32x32x16_bf16 v[48:63], v[216:219], v[160:163], v[48:63]
	ds_read_b64_tr_b16 v[216:217], v186 offset:0x400
	ds_read_b64_tr_b16 v[218:219], v186 offset:0xc00
	v_mfma_f32_32x32x16_bf16 v[48:63], v[220:223], v[164:167], v[48:63]
	ds_read_b64_tr_b16 v[220:221], v186 offset:0x1400
	ds_read_b64_tr_b16 v[222:223], v186 offset:0x1c00
	v_mfma_f32_32x32x16_bf16 v[48:63], v[224:227], v[170:173], v[48:63]
	ds_read_b64_tr_b16 v[224:225], v186 offset:0x2400
	ds_read_b64_tr_b16 v[226:227], v186 offset:0x2c00
	v_mfma_f32_32x32x16_bf16 v[48:63], v[228:231], v[212:215], v[48:63]
	ds_read_b64_tr_b16 v[228:229], v186 offset:0x3400
	ds_read_b64_tr_b16 v[230:231], v186 offset:0x3c00
	s_waitcnt lgkmcnt(0)
	v_mfma_f32_32x32x16_bf16 v[32:47], v[216:219], v[160:163], v[32:47]
	ds_read_b64_tr_b16 v[216:217], v186 offset:0x600
	ds_read_b64_tr_b16 v[218:219], v186 offset:0xe00
	v_mfma_f32_32x32x16_bf16 v[32:47], v[220:223], v[164:167], v[32:47]
	ds_read_b64_tr_b16 v[220:221], v186 offset:0x1600
	ds_read_b64_tr_b16 v[222:223], v186 offset:0x1e00
	v_mfma_f32_32x32x16_bf16 v[32:47], v[224:227], v[170:173], v[32:47]
	ds_read_b64_tr_b16 v[224:225], v186 offset:0x2600
	ds_read_b64_tr_b16 v[226:227], v186 offset:0x2e00
	v_mfma_f32_32x32x16_bf16 v[32:47], v[228:231], v[212:215], v[32:47]
	ds_read_b64_tr_b16 v[228:229], v186 offset:0x3600
	ds_read_b64_tr_b16 v[230:231], v186 offset:0x3e00
	s_waitcnt lgkmcnt(0)
	v_mfma_f32_32x32x16_bf16 v[16:31], v[216:219], v[160:163], v[16:31]
	v_max_f32_e32 v160, v81, v81
	v_max_f32_e32 v161, v80, v80
	v_max_f32_e32 v160, v161, v160
	v_max3_f32 v160, v160, v82, v83
	v_max3_f32 v160, v160, v84, v85
	v_max3_f32 v160, v160, v86, v87
	v_max3_f32 v160, v160, v88, v89
	v_max3_f32 v160, v160, v90, v91
	v_max3_f32 v160, v160, v92, v93
	v_mfma_f32_32x32x16_bf16 v[16:31], v[220:223], v[164:167], v[16:31]
	v_max3_f32 v160, v160, v94, v95
	v_max3_f32 v160, v160, v64, v65
	v_max3_f32 v160, v160, v66, v67
	v_max3_f32 v160, v160, v68, v69
	v_max3_f32 v160, v160, v70, v71
	v_max3_f32 v160, v160, v72, v73
	v_max3_f32 v160, v160, v74, v75
	v_max3_f32 v160, v160, v76, v77
	v_mfma_f32_32x32x16_bf16 v[16:31], v[224:227], v[170:173], v[16:31]
	v_max3_f32 v160, v160, v78, v79
	v_mov_b32_e32 v161, v160
	s_nop 1
	v_permlane32_swap_b32_e32 v160, v161
	v_max_f32_e32 v161, v161, v161
	v_max_f32_e32 v160, v160, v160
	v_max_f32_e32 v160, v160, v161
	v_sub_f32_e32 v161, v160, v168
	v_cmp_ge_f32_e32 vcc, s59, v161
	v_max_f32_e32 v161, v168, v168
	v_max_f32_e32 v160, v161, v160
	v_mfma_f32_32x32x16_bf16 v[16:31], v[228:231], v[212:215], v[16:31]
	v_sub_f32_e32 v161, v168, v160
	v_mul_f32_e32 v161, 0x3e0293ee, v161
	v_exp_f32_e32 v161, v161
	s_cmp_eq_u64 vcc, exec
	s_cselect_b64 s[0:1], -1, 0
	s_barrier
	s_waitcnt vmcnt(4)
	v_cndmask_b32_e64 v211, v161, 1.0, s[0:1]
	v_cmp_gt_f32_e32 vcc, 1.0, v211
	s_waitcnt vmcnt(4)
	ds_write_b128 v189, v[132:135]
	ds_write_b128 v190, v[140:143]
	ds_write_b128 v187, v[128:131] offset:32768
	ds_write_b128 v188, v[136:139] offset:32768
	s_cbranch_vccz .LBB0_194
	s_nop 7
	s_nop 7
	v_mul_f32_e32 v0, v211, v0
	v_mul_f32_e32 v1, v211, v1
	v_mul_f32_e32 v2, v211, v2
	v_mul_f32_e32 v3, v211, v3
	v_mul_f32_e32 v4, v211, v4
	v_mul_f32_e32 v5, v211, v5
	v_mul_f32_e32 v6, v211, v6
	v_mul_f32_e32 v7, v211, v7
	v_mul_f32_e32 v8, v211, v8
	v_mul_f32_e32 v9, v211, v9
	v_mul_f32_e32 v10, v211, v10
	v_mul_f32_e32 v11, v211, v11
	v_mul_f32_e32 v12, v211, v12
	v_mul_f32_e32 v13, v211, v13
	v_mul_f32_e32 v14, v211, v14
	v_mul_f32_e32 v15, v211, v15
	v_mul_f32_e32 v48, v211, v48
	v_mul_f32_e32 v49, v211, v49
	v_mul_f32_e32 v50, v211, v50
	v_mul_f32_e32 v51, v211, v51
	v_mul_f32_e32 v52, v211, v52
	v_mul_f32_e32 v53, v211, v53
	v_mul_f32_e32 v54, v211, v54
	v_mul_f32_e32 v55, v211, v55
	v_mul_f32_e32 v56, v211, v56
	v_mul_f32_e32 v57, v211, v57
	v_mul_f32_e32 v58, v211, v58
	v_mul_f32_e32 v59, v211, v59
	v_mul_f32_e32 v60, v211, v60
	v_mul_f32_e32 v61, v211, v61
	v_mul_f32_e32 v62, v211, v62
	v_mul_f32_e32 v63, v211, v63
	v_mul_f32_e32 v32, v211, v32
	v_mul_f32_e32 v33, v211, v33
	v_mul_f32_e32 v34, v211, v34
	v_mul_f32_e32 v35, v211, v35
	v_mul_f32_e32 v36, v211, v36
	v_mul_f32_e32 v37, v211, v37
	v_mul_f32_e32 v38, v211, v38
	v_mul_f32_e32 v39, v211, v39
	v_mul_f32_e32 v40, v211, v40
	v_mul_f32_e32 v41, v211, v41
	v_mul_f32_e32 v42, v211, v42
	v_mul_f32_e32 v43, v211, v43
	v_mul_f32_e32 v44, v211, v44
	v_mul_f32_e32 v45, v211, v45
	v_mul_f32_e32 v46, v211, v46
	v_mul_f32_e32 v47, v211, v47
	v_mul_f32_e32 v16, v211, v16
	v_mul_f32_e32 v17, v211, v17
	v_mul_f32_e32 v18, v211, v18
	v_mul_f32_e32 v19, v211, v19
	v_mul_f32_e32 v20, v211, v20
	v_mul_f32_e32 v21, v211, v21
	v_mul_f32_e32 v22, v211, v22
	v_mul_f32_e32 v23, v211, v23
	v_mul_f32_e32 v24, v211, v24
	v_mul_f32_e32 v25, v211, v25
	v_mul_f32_e32 v26, v211, v26
	v_mul_f32_e32 v27, v211, v27
	v_mul_f32_e32 v28, v211, v28
	v_mul_f32_e32 v29, v211, v29
	v_mul_f32_e32 v30, v211, v30
	v_mul_f32_e32 v31, v211, v31

; #define SBAR() __builtin_amdgcn_sched_barrier(0)
; __device__ __forceinline__ void partialSM(f32x16& p0, f32x16& p1, float& m_reg, float& mn, float& alpha) {
;   constexpr float C = AT_SCALE * 1.4426950408889634f;
;   float pmax = p0[0];
; #pragma unroll
;   for (int r = 1; r < 16; ++r) pmax = fmaxf(pmax, p0[r]);
; #pragma unroll
;   for (int r = 0; r < 16; ++r) pmax = fmaxf(pmax, p1[r]);
;   { auto rr = __builtin_amdgcn_permlane32_swap(__float_as_uint(pmax), __float_as_uint(pmax), false, false);
;     pmax = fmaxf(__uint_as_float(rr[0]), __uint_as_float(rr[1])); }
;   if (__builtin_expect(__all(pmax - m_reg <= AT_THR / AT_SCALE), 1)) { mn = m_reg; alpha = 1.f; }
;   else { mn = fmaxf(m_reg, pmax); alpha = __builtin_amdgcn_exp2f((m_reg - mn) * C); m_reg = mn; }
; template <int D0> __device__ __forceinline__ void pv_one(f32x16& od, int vb, bf16x8 pa0, bf16x8 pa1, bf16x8 pa2, bf16x8 pa3) {
;   const s16x4 l0 = tr_read<v_rd_off(D0, 0, 0)>(vb), h0 = tr_read<v_rd_off(D0, 0, 1)>(vb), l1 = tr_read<v_rd_off(D0, 1, 0)>(vb), h1 = tr_read<v_rd_off(D0, 1, 1)>(vb);
;   const s16x4 l2 = tr_read<v_rd_off(D0, 2, 0)>(vb), h2 = tr_read<v_rd_off(D0, 2, 1)>(vb), l3 = tr_read<v_rd_off(D0, 3, 0)>(vb), h3 = tr_read<v_rd_off(D0, 3, 1)>(vb);
;   asm volatile("s_waitcnt lgkmcnt(0)" ::: "memory"); SBAR();
;     ...
;   od = __builtin_amdgcn_mfma_f32_32x32x16_bf16(pa0, PK(l0, h0), od, 0, 0, 0);
;   od = __builtin_amdgcn_mfma_f32_32x32x16_bf16(pa1, PK(l1, h1), od, 0, 0, 0);
;   od = __builtin_amdgcn_mfma_f32_32x32x16_bf16(pa2, PK(l2, h2), od, 0, 0, 0);
;   od = __builtin_amdgcn_mfma_f32_32x32x16_bf16(pa3, PK(l3, h3), od, 0, 0, 0);
;     ...
; }
.LBB0_196:
	ds_read_b64_tr_b16 v[216:217], v185 offset:0
	ds_read_b64_tr_b16 v[218:219], v185 offset:0x800
	ds_read_b64_tr_b16 v[220:221], v185 offset:0x1000
	ds_read_b64_tr_b16 v[222:223], v185 offset:0x1800
	ds_read_b64_tr_b16 v[224:225], v185 offset:0x2000
	ds_read_b64_tr_b16 v[226:227], v185 offset:0x2800
	ds_read_b64_tr_b16 v[228:229], v185 offset:0x3000
	ds_read_b64_tr_b16 v[230:231], v185 offset:0x3800
	s_waitcnt lgkmcnt(0)
	s_nop 0
	v_mfma_f32_32x32x16_bf16 v[0:15], v[216:219], v[160:163], v[0:15]
	ds_read_b64_tr_b16 v[216:217], v185 offset:0x200
	ds_read_b64_tr_b16 v[218:219], v185 offset:0xa00
	v_mfma_f32_32x32x16_bf16 v[0:15], v[220:223], v[164:167], v[0:15]
	ds_read_b64_tr_b16 v[220:221], v185 offset:0x1200
	ds_read_b64_tr_b16 v[222:223], v185 offset:0x1a00
	v_mfma_f32_32x32x16_bf16 v[0:15], v[224:227], v[168:171], v[0:15]
	ds_read_b64_tr_b16 v[224:225], v185 offset:0x2200
	ds_read_b64_tr_b16 v[226:227], v185 offset:0x2a00
	v_mfma_f32_32x32x16_bf16 v[0:15], v[228:231], v[172:175], v[0:15]
	ds_read_b64_tr_b16 v[228:229], v185 offset:0x3200
	ds_read_b64_tr_b16 v[230:231], v185 offset:0x3a00
	s_waitcnt lgkmcnt(0)
	v_mfma_f32_32x32x16_bf16 v[48:63], v[216:219], v[160:163], v[48:63]
	ds_read_b64_tr_b16 v[216:217], v185 offset:0x400
	ds_read_b64_tr_b16 v[218:219], v185 offset:0xc00
	v_mfma_f32_32x32x16_bf16 v[48:63], v[220:223], v[164:167], v[48:63]
	ds_read_b64_tr_b16 v[220:221], v185 offset:0x1400
	ds_read_b64_tr_b16 v[222:223], v185 offset:0x1c00
	v_mfma_f32_32x32x16_bf16 v[48:63], v[224:227], v[168:171], v[48:63]
	ds_read_b64_tr_b16 v[224:225], v185 offset:0x2400
	ds_read_b64_tr_b16 v[226:227], v185 offset:0x2c00
	v_mfma_f32_32x32x16_bf16 v[48:63], v[228:231], v[172:175], v[48:63]
	ds_read_b64_tr_b16 v[228:229], v185 offset:0x3400
	ds_read_b64_tr_b16 v[230:231], v185 offset:0x3c00
	s_waitcnt lgkmcnt(0)
	v_mfma_f32_32x32x16_bf16 v[32:47], v[216:219], v[160:163], v[32:47]
	ds_read_b64_tr_b16 v[216:217], v185 offset:0x600
	ds_read_b64_tr_b16 v[218:219], v185 offset:0xe00
	v_mfma_f32_32x32x16_bf16 v[32:47], v[220:223], v[164:167], v[32:47]
	ds_read_b64_tr_b16 v[220:221], v185 offset:0x1600
	ds_read_b64_tr_b16 v[222:223], v185 offset:0x1e00
	v_mfma_f32_32x32x16_bf16 v[32:47], v[224:227], v[168:171], v[32:47]
	ds_read_b64_tr_b16 v[224:225], v185 offset:0x2600
	ds_read_b64_tr_b16 v[226:227], v185 offset:0x2e00
	v_mfma_f32_32x32x16_bf16 v[32:47], v[228:231], v[172:175], v[32:47]
	ds_read_b64_tr_b16 v[228:229], v185 offset:0x3600
	ds_read_b64_tr_b16 v[230:231], v185 offset:0x3e00
	s_waitcnt lgkmcnt(0)
	v_mfma_f32_32x32x16_bf16 v[16:31], v[216:219], v[160:163], v[16:31]
	v_max_f32_e32 v160, v81, v81
	v_max_f32_e32 v161, v80, v80
	v_max_f32_e32 v160, v161, v160
	v_max3_f32 v160, v160, v82, v83
	v_max3_f32 v160, v160, v84, v85
	v_max3_f32 v160, v160, v86, v87
	v_max3_f32 v160, v160, v88, v89
	v_max3_f32 v160, v160, v90, v91
	v_max3_f32 v160, v160, v92, v93
	v_mfma_f32_32x32x16_bf16 v[16:31], v[220:223], v[164:167], v[16:31]
	v_max3_f32 v160, v160, v94, v95
	v_max3_f32 v160, v160, v64, v65
	v_max3_f32 v160, v160, v66, v67
	v_max3_f32 v160, v160, v68, v69
	v_max3_f32 v160, v160, v70, v71
	v_max3_f32 v160, v160, v72, v73
	v_max3_f32 v160, v160, v74, v75
	v_max3_f32 v160, v160, v76, v77
	v_mfma_f32_32x32x16_bf16 v[16:31], v[224:227], v[168:171], v[16:31]
	v_max3_f32 v160, v160, v78, v79
	v_mov_b32_e32 v161, v160
	s_nop 1
	v_permlane32_swap_b32_e32 v160, v161
	v_max_f32_e32 v161, v161, v161
	v_max_f32_e32 v160, v160, v160
	v_max_f32_e32 v160, v160, v161
	v_sub_f32_e32 v161, v160, v212
	v_cmp_ge_f32_e32 vcc, s59, v161
	v_max_f32_e32 v161, v212, v212
	v_max_f32_e32 v161, v161, v160
	v_mfma_f32_32x32x16_bf16 v[16:31], v[228:231], v[172:175], v[16:31]
	v_sub_f32_e32 v160, v212, v161
	v_mul_f32_e32 v160, 0x3e0293ee, v160
	v_exp_f32_e32 v160, v160
	s_cmp_eq_u64 vcc, exec
	s_cselect_b64 s[0:1], -1, 0
	s_barrier
	s_waitcnt vmcnt(4)
	v_cndmask_b32_e64 v160, v160, 1.0, s[0:1]
	v_cmp_gt_f32_e32 vcc, 1.0, v160
	s_waitcnt vmcnt(3)
	ds_write_b128 v189, v[144:147] offset:16384
	s_waitcnt vmcnt(2)
	ds_write_b128 v190, v[148:151] offset:16384
	s_waitcnt vmcnt(1)
	ds_write_b128 v187, v[152:155] offset:49152
	s_waitcnt vmcnt(0)
	ds_write_b128 v188, v[156:159] offset:49152
	s_cbranch_vccz .LBB0_200
	s_nop 7
	s_nop 7
	v_mul_f32_e32 v0, v160, v0
	v_mul_f32_e32 v1, v160, v1
	v_mul_f32_e32 v2, v160, v2
	v_mul_f32_e32 v3, v160, v3
	v_mul_f32_e32 v4, v160, v4
	v_mul_f32_e32 v5, v160, v5
	v_mul_f32_e32 v6, v160, v6
	v_mul_f32_e32 v7, v160, v7
	v_mul_f32_e32 v8, v160, v8
	v_mul_f32_e32 v9, v160, v9
	v_mul_f32_e32 v10, v160, v10
	v_mul_f32_e32 v11, v160, v11
	v_mul_f32_e32 v12, v160, v12
	v_mul_f32_e32 v13, v160, v13
	v_mul_f32_e32 v14, v160, v14
	v_mul_f32_e32 v15, v160, v15
	v_mul_f32_e32 v48, v160, v48
	v_mul_f32_e32 v49, v160, v49
	v_mul_f32_e32 v50, v160, v50
	v_mul_f32_e32 v51, v160, v51
	v_mul_f32_e32 v52, v160, v52
	v_mul_f32_e32 v53, v160, v53
	v_mul_f32_e32 v54, v160, v54
	v_mul_f32_e32 v55, v160, v55
	v_mul_f32_e32 v56, v160, v56
	v_mul_f32_e32 v57, v160, v57
	v_mul_f32_e32 v58, v160, v58
	v_mul_f32_e32 v59, v160, v59
	v_mul_f32_e32 v60, v160, v60
	v_mul_f32_e32 v61, v160, v61
	v_mul_f32_e32 v62, v160, v62
	v_mul_f32_e32 v63, v160, v63
	v_mul_f32_e32 v32, v160, v32
	v_mul_f32_e32 v33, v160, v33
	v_mul_f32_e32 v34, v160, v34
	v_mul_f32_e32 v35, v160, v35
	v_mul_f32_e32 v36, v160, v36
	v_mul_f32_e32 v37, v160, v37
	v_mul_f32_e32 v38, v160, v38
	v_mul_f32_e32 v39, v160, v39
	v_mul_f32_e32 v40, v160, v40
	v_mul_f32_e32 v41, v160, v41
	v_mul_f32_e32 v42, v160, v42
	v_mul_f32_e32 v43, v160, v43
	v_mul_f32_e32 v44, v160, v44
	v_mul_f32_e32 v45, v160, v45
	v_mul_f32_e32 v46, v160, v46
	v_mul_f32_e32 v47, v160, v47
	v_mul_f32_e32 v16, v160, v16
	v_mul_f32_e32 v17, v160, v17
	v_mul_f32_e32 v18, v160, v18
	v_mul_f32_e32 v19, v160, v19
	v_mul_f32_e32 v20, v160, v20
	v_mul_f32_e32 v21, v160, v21
	v_mul_f32_e32 v22, v160, v22
	v_mul_f32_e32 v23, v160, v23
	v_mul_f32_e32 v24, v160, v24
	v_mul_f32_e32 v25, v160, v25
	v_mul_f32_e32 v26, v160, v26
	v_mul_f32_e32 v27, v160, v27
	v_mul_f32_e32 v28, v160, v28
	v_mul_f32_e32 v29, v160, v29
	v_mul_f32_e32 v30, v160, v30
	v_mul_f32_e32 v31, v160, v31

; #define SBAR() __builtin_amdgcn_sched_barrier(0)
; __device__ __forceinline__ void finishSM(f32x16& p0, f32x16& p1, float alpha, float& l_reg, bf16x8& pa0, bf16x8& pa1, bf16x8& pa2, bf16x8& pa3) {
; #pragma unroll
;   for (int r = 0; r < 16; ++r) p1[r] = __builtin_amdgcn_exp2f(p1[r]);
;   float ps = 0;
; #pragma unroll
;   for (int r = 0; r < 16; ++r) ps += p0[r];
; #pragma unroll
;   for (int r = 0; r < 16; ++r) ps += p1[r];
;   { auto rr = __builtin_amdgcn_permlane32_swap(__float_as_uint(ps), __float_as_uint(ps), false, false);
;     ps = __uint_as_float(rr[0]) + __uint_as_float(rr[1]); }
;   l_reg = l_reg * alpha + ps;
;     ...
;   PK4(p0, 0, pa0); PK4(p0, 8, pa1); PK4(p1, 0, pa2); PK4(p1, 8, pa3);
;     ...
; }
; __device__ __forceinline__ void qkt(f32x16& p0, f32x16& p1, const char* Ks, const bf16x8* qr, int r32, int hi) {
; #pragma unroll
;   for (int r = 0; r < 16; ++r) { p0[r] = 0.f; p1[r] = 0.f; }
; #pragma unroll
;   for (int d0 = 0; d0 < 8; ++d0) { int cb = (d0 * 16 + hi * 8) * 2;
;     bf16x8 b0 = *reinterpret_cast<const bf16x8*>(Ks + KSWZ(r32, cb));
;     bf16x8 b1 = *reinterpret_cast<const bf16x8*>(Ks + KSWZ(32 + r32, cb));
;     p0 = __builtin_amdgcn_mfma_f32_32x32x16_bf16(b0, qr[d0], p0, 0, 0, 0);
;     p1 = __builtin_amdgcn_mfma_f32_32x32x16_bf16(b1, qr[d0], p1, 0, 0, 0); }
; }
; __device__ __forceinline__ int v_st(int k, int c) { const int kk = (k & ~0xC) | ((k & 4) << 1) | ((k & 8) >> 1); return ((kk >> 3) * 4 + (c >> 5)) * 512 + ((kk & 7) * 32 + (c & 31)) * 2; }
; __device__ __forceinline__ int v_rd_base(int lane) { return ((lane & 3) << 3) | (((lane >> 2) & 3) << 6) | (((lane >> 4) & 1) << 5) | (((lane >> 5) & 1) << 8); }
; template <int OFF> __device__ __forceinline__ s16x4 tr_read(int vb) {
;   s16x4 r; asm volatile("ds_read_b64_tr_b16 %0, %1 offset:%2" : "=&v"(r) : "v"(vb), "i"(OFF) : "memory"); return r;
; }
; template <int D0> __device__ __forceinline__ void pv_one(f32x16& od, int vb, bf16x8 pa0, bf16x8 pa1, bf16x8 pa2, bf16x8 pa3) {
;   const s16x4 l0 = tr_read<v_rd_off(D0, 0, 0)>(vb), h0 = tr_read<v_rd_off(D0, 0, 1)>(vb), l1 = tr_read<v_rd_off(D0, 1, 0)>(vb), h1 = tr_read<v_rd_off(D0, 1, 1)>(vb);
;   const s16x4 l2 = tr_read<v_rd_off(D0, 2, 0)>(vb), h2 = tr_read<v_rd_off(D0, 2, 1)>(vb), l3 = tr_read<v_rd_off(D0, 3, 0)>(vb), h3 = tr_read<v_rd_off(D0, 3, 1)>(vb);
;   asm volatile("s_waitcnt lgkmcnt(0)" ::: "memory"); SBAR();
.LBB0_202:
	ds_read_b128 v[64:67], v191 offset:49152
	ds_read_b128 v[68:71], v191 offset:57344
	s_waitcnt lgkmcnt(1)
	v_mfma_f32_32x32x16_bf16 v[80:95], v[64:67], v[116:119], 0
	s_waitcnt lgkmcnt(0)
	v_mfma_f32_32x32x16_bf16 v[64:79], v[68:71], v[116:119], 0
	ds_read_b128 v[116:119], v196 offset:49152
	ds_read_b128 v[128:131], v196 offset:57344
	s_waitcnt lgkmcnt(1)
	v_mfma_f32_32x32x16_bf16 v[80:95], v[116:119], v[108:111], v[80:95]
	s_waitcnt lgkmcnt(0)
	v_mfma_f32_32x32x16_bf16 v[64:79], v[128:131], v[108:111], v[64:79]
	ds_read_b128 v[108:111], v195 offset:49152
	ds_read_b128 v[116:119], v195 offset:57344
	s_waitcnt lgkmcnt(1)
	v_mfma_f32_32x32x16_bf16 v[80:95], v[108:111], v[124:127], v[80:95]
	s_waitcnt lgkmcnt(0)
	v_mfma_f32_32x32x16_bf16 v[64:79], v[116:119], v[124:127], v[64:79]
	ds_read_b128 v[108:111], v194 offset:49152
	ds_read_b128 v[116:119], v194 offset:57344
	s_waitcnt lgkmcnt(1)
	v_mfma_f32_32x32x16_bf16 v[80:95], v[108:111], v[120:123], v[80:95]
	s_waitcnt lgkmcnt(0)
	v_mfma_f32_32x32x16_bf16 v[64:79], v[116:119], v[120:123], v[64:79]
	ds_read_b128 v[108:111], v193 offset:49152
	ds_read_b128 v[116:119], v193 offset:57344
	v_exp_f32_e32 v120, v144
	v_exp_f32_e32 v121, v145
	s_waitcnt lgkmcnt(1)
	v_mfma_f32_32x32x16_bf16 v[80:95], v[108:111], v[112:115], v[80:95]
	s_waitcnt lgkmcnt(0)
	v_mfma_f32_32x32x16_bf16 v[64:79], v[116:119], v[112:115], v[64:79]
	ds_read_b128 v[108:111], v192 offset:49152
	ds_read_b128 v[112:115], v192 offset:57344
	v_exp_f32_e32 v116, v154
	v_exp_f32_e32 v117, v155
	v_exp_f32_e32 v118, v150
	v_exp_f32_e32 v119, v151
	s_waitcnt lgkmcnt(1)
	v_mfma_f32_32x32x16_bf16 v[80:95], v[108:111], v[104:107], v[80:95]
	s_waitcnt lgkmcnt(0)
	v_mfma_f32_32x32x16_bf16 v[64:79], v[112:115], v[104:107], v[64:79]
	ds_read_b128 v[104:107], v198 offset:49152
	ds_read_b128 v[108:111], v198 offset:57344
	v_exp_f32_e32 v112, v148
	v_exp_f32_e32 v113, v149
	v_exp_f32_e32 v114, v146
	v_exp_f32_e32 v115, v147
	s_waitcnt lgkmcnt(1)
	v_mfma_f32_32x32x16_bf16 v[80:95], v[104:107], v[100:103], v[80:95]
	s_waitcnt lgkmcnt(0)
	v_mfma_f32_32x32x16_bf16 v[64:79], v[108:111], v[100:103], v[64:79]
	ds_read_b128 v[100:103], v197 offset:49152
	ds_read_b128 v[104:107], v197 offset:57344
	v_exp_f32_e32 v108, v156
	v_exp_f32_e32 v109, v157
	v_exp_f32_e32 v110, v152
	v_exp_f32_e32 v111, v153
	s_waitcnt lgkmcnt(1)
	v_mfma_f32_32x32x16_bf16 v[80:95], v[100:103], v[96:99], v[80:95]
	s_waitcnt lgkmcnt(0)
	v_mfma_f32_32x32x16_bf16 v[64:79], v[104:107], v[96:99], v[64:79]
	v_add_f32_e32 v96, 0, v161
	v_add_f32_e32 v96, v175, v96
	v_add_f32_e32 v96, v162, v96
	v_add_f32_e32 v96, v212, v96
	v_add_f32_e32 v96, v174, v96
	v_add_f32_e32 v96, v215, v96
	v_add_f32_e32 v96, v163, v96
	v_add_f32_e32 v96, v173, v96
	v_add_f32_e32 v96, v164, v96
	v_add_f32_e32 v96, v171, v96
	v_add_f32_e32 v96, v165, v96
	v_add_f32_e32 v96, v172, v96
	v_exp_f32_e32 v106, v158
	v_add_f32_e32 v96, v166, v96
	v_exp_f32_e32 v107, v159
	v_add_f32_e32 v96, v169, v96
	v_add_f32_e32 v96, v167, v96
	v_add_f32_e32 v96, v170, v96
	v_add_f32_e32 v96, v106, v96
	v_add_f32_e32 v96, v107, v96
	v_add_f32_e32 v96, v108, v96
	v_add_f32_e32 v96, v109, v96
	v_add_f32_e32 v96, v110, v96
	v_add_f32_e32 v96, v111, v96
	v_add_f32_e32 v96, v112, v96
	v_add_f32_e32 v96, v113, v96
	v_add_f32_e32 v96, v114, v96
	v_add_f32_e32 v96, v115, v96
	v_add_f32_e32 v96, v116, v96
	v_add_f32_e32 v96, v117, v96
	v_add_f32_e32 v96, v118, v96
	v_add_f32_e32 v96, v119, v96
	v_add_f32_e32 v96, v120, v96
	v_add_f32_e32 v100, v121, v96
	v_mov_b32_e32 v101, v100
	v_cvt_pk_bf16_f32 v96, v161, v175
	v_cvt_pk_bf16_f32 v97, v162, v212
	v_cvt_pk_bf16_f32 v98, v174, v215
	v_cvt_pk_bf16_f32 v99, v163, v173
	s_nop 1
	v_permlane32_swap_b32_e32 v100, v101
	v_permlane32_swap_b32_e32 v96, v98
	v_permlane32_swap_b32_e32 v97, v99
	v_cvt_pk_bf16_f32 v102, v164, v171
	v_cvt_pk_bf16_f32 v103, v165, v172
	v_cvt_pk_bf16_f32 v104, v166, v169
	v_cvt_pk_bf16_f32 v105, v167, v170
	v_cvt_pk_bf16_f32 v106, v106, v107
	v_cvt_pk_bf16_f32 v107, v108, v109
	v_cvt_pk_bf16_f32 v108, v110, v111
	v_cvt_pk_bf16_f32 v109, v112, v113
	v_cvt_pk_bf16_f32 v110, v114, v115
	v_cvt_pk_bf16_f32 v111, v116, v117
	v_cvt_pk_bf16_f32 v112, v118, v119
	v_cvt_pk_bf16_f32 v113, v120, v121
	s_nop 0
	v_permlane32_swap_b32_e32 v102, v104
	v_permlane32_swap_b32_e32 v103, v105
	v_permlane32_swap_b32_e32 v106, v108
	v_permlane32_swap_b32_e32 v107, v109
	v_permlane32_swap_b32_e32 v110, v112
	v_permlane32_swap_b32_e32 v111, v113
	ds_read_b64_tr_b16 v[114:115], v186 offset:0
	ds_read_b64_tr_b16 v[116:117], v186 offset:0x800
	ds_read_b64_tr_b16 v[118:119], v186 offset:0x1000
	ds_read_b64_tr_b16 v[120:121], v186 offset:0x1800
	ds_read_b64_tr_b16 v[122:123], v186 offset:0x2000
	ds_read_b64_tr_b16 v[124:125], v186 offset:0x2800
	ds_read_b64_tr_b16 v[126:127], v186 offset:0x3000
	ds_read_b64_tr_b16 v[128:129], v186 offset:0x3800
	s_waitcnt lgkmcnt(0)
	s_nop 0
	v_mfma_f32_32x32x16_bf16 v[0:15], v[114:117], v[96:99], v[0:15]
	ds_read_b64_tr_b16 v[114:115], v186 offset:0x200
	ds_read_b64_tr_b16 v[116:117], v186 offset:0xa00
	v_mfma_f32_32x32x16_bf16 v[0:15], v[118:121], v[102:105], v[0:15]
	ds_read_b64_tr_b16 v[118:119], v186 offset:0x1200
	ds_read_b64_tr_b16 v[120:121], v186 offset:0x1a00
	v_mfma_f32_32x32x16_bf16 v[0:15], v[122:125], v[106:109], v[0:15]
	ds_read_b64_tr_b16 v[122:123], v186 offset:0x2200
	ds_read_b64_tr_b16 v[124:125], v186 offset:0x2a00
	v_mfma_f32_32x32x16_bf16 v[0:15], v[126:129], v[110:113], v[0:15]
	ds_read_b64_tr_b16 v[126:127], v186 offset:0x3200
	ds_read_b64_tr_b16 v[128:129], v186 offset:0x3a00
	s_waitcnt lgkmcnt(0)
; #define SBAR() __builtin_amdgcn_sched_barrier(0)
; __device__ __forceinline__ void partialSM(f32x16& p0, f32x16& p1, float& m_reg, float& mn, float& alpha) {
;   constexpr float C = AT_SCALE * 1.4426950408889634f;
;   float pmax = p0[0];
; #pragma unroll
;   for (int r = 1; r < 16; ++r) pmax = fmaxf(pmax, p0[r]);
; #pragma unroll
;   for (int r = 0; r < 16; ++r) pmax = fmaxf(pmax, p1[r]);
;   { auto rr = __builtin_amdgcn_permlane32_swap(__float_as_uint(pmax), __float_as_uint(pmax), false, false);
;     pmax = fmaxf(__uint_as_float(rr[0]), __uint_as_float(rr[1])); }
;   if (__builtin_expect(__all(pmax - m_reg <= AT_THR / AT_SCALE), 1)) { mn = m_reg; alpha = 1.f; }
;   else { mn = fmaxf(m_reg, pmax); alpha = __builtin_amdgcn_exp2f((m_reg - mn) * C); m_reg = mn; }
; template <int D0> __device__ __forceinline__ void pv_one(f32x16& od, int vb, bf16x8 pa0, bf16x8 pa1, bf16x8 pa2, bf16x8 pa3) {
;   const s16x4 l0 = tr_read<v_rd_off(D0, 0, 0)>(vb), h0 = tr_read<v_rd_off(D0, 0, 1)>(vb), l1 = tr_read<v_rd_off(D0, 1, 0)>(vb), h1 = tr_read<v_rd_off(D0, 1, 1)>(vb);
;   const s16x4 l2 = tr_read<v_rd_off(D0, 2, 0)>(vb), h2 = tr_read<v_rd_off(D0, 2, 1)>(vb), l3 = tr_read<v_rd_off(D0, 3, 0)>(vb), h3 = tr_read<v_rd_off(D0, 3, 1)>(vb);
;   asm volatile("s_waitcnt lgkmcnt(0)" ::: "memory"); SBAR();
;     ...
;   od = __builtin_amdgcn_mfma_f32_32x32x16_bf16(pa0, PK(l0, h0), od, 0, 0, 0);
;   od = __builtin_amdgcn_mfma_f32_32x32x16_bf16(pa1, PK(l1, h1), od, 0, 0, 0);
;   od = __builtin_amdgcn_mfma_f32_32x32x16_bf16(pa2, PK(l2, h2), od, 0, 0, 0);
;   od = __builtin_amdgcn_mfma_f32_32x32x16_bf16(pa3, PK(l3, h3), od, 0, 0, 0);
;     ...
; }
	v_mfma_f32_32x32x16_bf16 v[48:63], v[114:117], v[96:99], v[48:63]
	ds_read_b64_tr_b16 v[114:115], v186 offset:0x400
	ds_read_b64_tr_b16 v[116:117], v186 offset:0xc00
	v_mfma_f32_32x32x16_bf16 v[48:63], v[118:121], v[102:105], v[48:63]
	ds_read_b64_tr_b16 v[118:119], v186 offset:0x1400
	ds_read_b64_tr_b16 v[120:121], v186 offset:0x1c00
	v_mfma_f32_32x32x16_bf16 v[48:63], v[122:125], v[106:109], v[48:63]
	ds_read_b64_tr_b16 v[122:123], v186 offset:0x2400
	ds_read_b64_tr_b16 v[124:125], v186 offset:0x2c00
	v_mfma_f32_32x32x16_bf16 v[48:63], v[126:129], v[110:113], v[48:63]
	ds_read_b64_tr_b16 v[126:127], v186 offset:0x3400
	ds_read_b64_tr_b16 v[128:129], v186 offset:0x3c00
	s_waitcnt lgkmcnt(0)
	v_mfma_f32_32x32x16_bf16 v[32:47], v[114:117], v[96:99], v[32:47]
	ds_read_b64_tr_b16 v[114:115], v186 offset:0x600
	ds_read_b64_tr_b16 v[116:117], v186 offset:0xe00
	v_mfma_f32_32x32x16_bf16 v[32:47], v[118:121], v[102:105], v[32:47]
	ds_read_b64_tr_b16 v[118:119], v186 offset:0x1600
	ds_read_b64_tr_b16 v[120:121], v186 offset:0x1e00
	v_mfma_f32_32x32x16_bf16 v[32:47], v[122:125], v[106:109], v[32:47]
	ds_read_b64_tr_b16 v[122:123], v186 offset:0x2600
	ds_read_b64_tr_b16 v[124:125], v186 offset:0x2e00
	v_mfma_f32_32x32x16_bf16 v[32:47], v[126:129], v[110:113], v[32:47]
	ds_read_b64_tr_b16 v[126:127], v186 offset:0x3600
	ds_read_b64_tr_b16 v[128:129], v186 offset:0x3e00
	s_waitcnt lgkmcnt(0)
	v_mfma_f32_32x32x16_bf16 v[16:31], v[114:117], v[96:99], v[16:31]
	v_max_f32_e32 v96, v81, v81
	v_max_f32_e32 v97, v80, v80
	v_max_f32_e32 v96, v97, v96
	v_max3_f32 v96, v96, v82, v83
	v_max3_f32 v96, v96, v84, v85
	v_max3_f32 v96, v96, v86, v87
	v_max3_f32 v96, v96, v88, v89
	v_max3_f32 v96, v96, v90, v91
	v_max3_f32 v96, v96, v92, v93
	v_mfma_f32_32x32x16_bf16 v[16:31], v[118:121], v[102:105], v[16:31]
	v_max3_f32 v96, v96, v94, v95
	v_max3_f32 v96, v96, v64, v65
	v_max3_f32 v96, v96, v66, v67
	v_max3_f32 v96, v96, v68, v69
	v_max3_f32 v96, v96, v70, v71
	v_max3_f32 v96, v96, v72, v73
	v_max3_f32 v96, v96, v74, v75
	v_max3_f32 v96, v96, v76, v77
	v_mfma_f32_32x32x16_bf16 v[16:31], v[122:125], v[106:109], v[16:31]
	v_max3_f32 v96, v96, v78, v79
	v_mov_b32_e32 v97, v96
	s_nop 1
	v_permlane32_swap_b32_e32 v96, v97
	v_max_f32_e32 v97, v97, v97
	v_max_f32_e32 v96, v96, v96
	v_max_f32_e32 v96, v96, v97
	v_sub_f32_e32 v97, v96, v168
	v_cmp_ge_f32_e32 vcc, s59, v97
	v_max_f32_e32 v97, v168, v168
	v_max_f32_e32 v97, v97, v96
	v_mfma_f32_32x32x16_bf16 v[16:31], v[126:129], v[110:113], v[16:31]
	v_sub_f32_e32 v96, v168, v97
	v_mul_f32_e32 v96, 0x3e0293ee, v96
	v_exp_f32_e32 v96, v96
	s_cmp_eq_u64 vcc, exec
	s_cselect_b64 s[0:1], -1, 0
	v_cndmask_b32_e64 v96, v96, 1.0, s[0:1]
	v_cmp_gt_f32_e32 vcc, 1.0, v96
	s_barrier
	s_cbranch_vccz .LBB0_206
	s_nop 7
	s_nop 7
	v_mul_f32_e32 v0, v96, v0
	v_mul_f32_e32 v1, v96, v1
	v_mul_f32_e32 v2, v96, v2
	v_mul_f32_e32 v3, v96, v3
	v_mul_f32_e32 v4, v96, v4
	v_mul_f32_e32 v5, v96, v5
	v_mul_f32_e32 v6, v96, v6
	v_mul_f32_e32 v7, v96, v7
	v_mul_f32_e32 v8, v96, v8
	v_mul_f32_e32 v9, v96, v9
	v_mul_f32_e32 v10, v96, v10
	v_mul_f32_e32 v11, v96, v11
	v_mul_f32_e32 v12, v96, v12
	v_mul_f32_e32 v13, v96, v13
	v_mul_f32_e32 v14, v96, v14
	v_mul_f32_e32 v15, v96, v15
	v_mul_f32_e32 v48, v96, v48
	v_mul_f32_e32 v49, v96, v49
	v_mul_f32_e32 v50, v96, v50
	v_mul_f32_e32 v51, v96, v51
	v_mul_f32_e32 v52, v96, v52
	v_mul_f32_e32 v53, v96, v53
	v_mul_f32_e32 v54, v96, v54
	v_mul_f32_e32 v55, v96, v55
	v_mul_f32_e32 v56, v96, v56
	v_mul_f32_e32 v57, v96, v57
	v_mul_f32_e32 v58, v96, v58
	v_mul_f32_e32 v59, v96, v59
	v_mul_f32_e32 v60, v96, v60
	v_mul_f32_e32 v61, v96, v61
	v_mul_f32_e32 v62, v96, v62
	v_mul_f32_e32 v63, v96, v63
	v_mul_f32_e32 v32, v96, v32
	v_mul_f32_e32 v33, v96, v33
	v_mul_f32_e32 v34, v96, v34
	v_mul_f32_e32 v35, v96, v35
	v_mul_f32_e32 v36, v96, v36
	v_mul_f32_e32 v37, v96, v37
	v_mul_f32_e32 v38, v96, v38
	v_mul_f32_e32 v39, v96, v39
	v_mul_f32_e32 v40, v96, v40
	v_mul_f32_e32 v41, v96, v41
	v_mul_f32_e32 v42, v96, v42
	v_mul_f32_e32 v43, v96, v43
	v_mul_f32_e32 v44, v96, v44
	v_mul_f32_e32 v45, v96, v45
	v_mul_f32_e32 v46, v96, v46
	v_mul_f32_e32 v47, v96, v47
	v_mul_f32_e32 v16, v96, v16
	v_mul_f32_e32 v17, v96, v17
	v_mul_f32_e32 v18, v96, v18
	v_mul_f32_e32 v19, v96, v19
	v_mul_f32_e32 v20, v96, v20
	v_mul_f32_e32 v21, v96, v21
	v_mul_f32_e32 v22, v96, v22
	v_mul_f32_e32 v23, v96, v23
	v_mul_f32_e32 v24, v96, v24
	v_mul_f32_e32 v25, v96, v25
	v_mul_f32_e32 v26, v96, v26
	v_mul_f32_e32 v27, v96, v27
	v_mul_f32_e32 v28, v96, v28
	v_mul_f32_e32 v29, v96, v29
	v_mul_f32_e32 v30, v96, v30
	v_mul_f32_e32 v31, v96, v31
; #define SBAR() __builtin_amdgcn_sched_barrier(0)
; #define RESC(a) do { if (__any((a) < 1.f)) { if (hi == 0) al_l[r32] = (a); asm volatile("s_waitcnt lgkmcnt(0)" ::: "memory"); \
;     for (int d = 0; d < 4; ++d) for (int r = 0; r < 16; ++r) o[d][r] *= al_l[crow(r, hi)]; } } while (0)
; __device__ __forceinline__ void finishSM(f32x16& p0, f32x16& p1, float alpha, float& l_reg, bf16x8& pa0, bf16x8& pa1, bf16x8& pa2, bf16x8& pa3) {
; #pragma unroll
;   for (int r = 0; r < 16; ++r) p1[r] = __builtin_amdgcn_exp2f(p1[r]);
;   float ps = 0;
; #pragma unroll
;   for (int r = 0; r < 16; ++r) ps += p0[r];
; #pragma unroll
;   for (int r = 0; r < 16; ++r) ps += p1[r];
;   { auto rr = __builtin_amdgcn_permlane32_swap(__float_as_uint(ps), __float_as_uint(ps), false, false);
;     ps = __uint_as_float(rr[0]) + __uint_as_float(rr[1]); }
;   l_reg = l_reg * alpha + ps;
;     ...
;   PK4(p0, 0, pa0); PK4(p0, 8, pa1); PK4(p1, 0, pa2); PK4(p1, 8, pa3);
;     ...
; }
; __device__ __forceinline__ void attn_dense_body(const u16* __restrict__ Qb, const u16* __restrict__ Kh, const u16* __restrict__ Vh,
;                                                 u16* __restrict__ Ob, int seq, char* lds, int tid) {
;     ...
;   __syncthreads(); RESC(alB);
;   finishSM(pB0, pB1, alB, l_reg, pa0, pa1, pa2, pa3); SBAR();
;   pv_d0(o, vb0 + (int)SHM_V, pa0, pa1, pa2, pa3);
;   if (hi == 0) li_l[r32] = l_reg; asm volatile("s_waitcnt lgkmcnt(0)" ::: "memory");
.LBB0_206:
	v_cndmask_b32_e64 v97, v97, v168, s[0:1]
	v_mul_f32_e32 v97, 0xbe0293ee, v97
	v_fmamk_f32 v80, v80, 0x3e0293ee, v97
	v_fmamk_f32 v81, v81, 0x3e0293ee, v97
	v_fmamk_f32 v98, v82, 0x3e0293ee, v97
	v_exp_f32_e32 v82, v80
	v_fmamk_f32 v99, v84, 0x3e0293ee, v97
	v_exp_f32_e32 v84, v81
	v_fmamk_f32 v83, v83, 0x3e0293ee, v97
	v_exp_f32_e32 v80, v98
	v_fmamk_f32 v64, v64, 0x3e0293ee, v97
	v_exp_f32_e32 v83, v83
	v_fmamk_f32 v102, v85, 0x3e0293ee, v97
	v_fmamk_f32 v111, v94, 0x3e0293ee, v97
	v_fmamk_f32 v94, v75, 0x3e0293ee, v97
	v_exp_f32_e32 v75, v99
	v_exp_f32_e32 v98, v64
	v_add_f32_e32 v64, 0, v82
	v_fmamk_f32 v103, v86, 0x3e0293ee, v97
	v_exp_f32_e32 v81, v102
	v_add_f32_e32 v64, v84, v64
	v_fmamk_f32 v104, v87, 0x3e0293ee, v97
	v_fmamk_f32 v110, v93, 0x3e0293ee, v97
	v_fmamk_f32 v93, v74, 0x3e0293ee, v97
	v_exp_f32_e32 v74, v103
	v_add_f32_e32 v64, v80, v64
	v_fmamk_f32 v105, v88, 0x3e0293ee, v97
	v_fmamk_f32 v112, v95, 0x3e0293ee, v97
	v_fmamk_f32 v95, v76, 0x3e0293ee, v97
	v_exp_f32_e32 v76, v104
	v_add_f32_e32 v64, v83, v64
	v_fmamk_f32 v106, v89, 0x3e0293ee, v97
	v_fmamk_f32 v107, v90, 0x3e0293ee, v97
	v_fmamk_f32 v90, v71, 0x3e0293ee, v97
	v_exp_f32_e32 v71, v105
	v_add_f32_e32 v64, v75, v64
	v_fmamk_f32 v109, v92, 0x3e0293ee, v97
	v_fmamk_f32 v92, v73, 0x3e0293ee, v97
	v_exp_f32_e32 v73, v106
	v_add_f32_e32 v64, v81, v64
	v_fmamk_f32 v108, v91, 0x3e0293ee, v97
	v_fmamk_f32 v88, v69, 0x3e0293ee, v97
	v_exp_f32_e32 v69, v107
	v_add_f32_e32 v64, v74, v64
	v_fmamk_f32 v91, v72, 0x3e0293ee, v97
	v_exp_f32_e32 v72, v108
	v_add_f32_e32 v64, v76, v64
	v_fmamk_f32 v86, v67, 0x3e0293ee, v97
	v_exp_f32_e32 v67, v109
	v_add_f32_e32 v64, v71, v64
	v_fmamk_f32 v89, v70, 0x3e0293ee, v97
	v_exp_f32_e32 v70, v110
	v_add_f32_e32 v64, v73, v64
	v_fmamk_f32 v85, v66, 0x3e0293ee, v97
	v_exp_f32_e32 v66, v111
	v_add_f32_e32 v64, v69, v64
	v_fmamk_f32 v87, v68, 0x3e0293ee, v97
	v_exp_f32_e32 v68, v112
	v_add_f32_e32 v64, v72, v64
	v_fmamk_f32 v65, v65, 0x3e0293ee, v97
	v_add_f32_e32 v64, v67, v64
	v_exp_f32_e32 v99, v65
	v_add_f32_e32 v64, v70, v64
	v_exp_f32_e32 v85, v85
	v_add_f32_e32 v64, v66, v64
	v_exp_f32_e32 v86, v86
	v_add_f32_e32 v64, v68, v64
	v_exp_f32_e32 v87, v87
	v_add_f32_e32 v64, v98, v64
	v_exp_f32_e32 v88, v88
	v_add_f32_e32 v64, v99, v64
	v_exp_f32_e32 v89, v89
	v_add_f32_e32 v64, v85, v64
	v_exp_f32_e32 v90, v90
	v_add_f32_e32 v64, v86, v64
	v_exp_f32_e32 v91, v91
	v_add_f32_e32 v64, v87, v64
	v_exp_f32_e32 v92, v92
	v_add_f32_e32 v64, v88, v64
	v_exp_f32_e32 v93, v93
	v_add_f32_e32 v64, v89, v64
	v_exp_f32_e32 v94, v94
	v_add_f32_e32 v64, v90, v64
	v_fmamk_f32 v77, v77, 0x3e0293ee, v97
	v_exp_f32_e32 v95, v95
	v_add_f32_e32 v64, v91, v64
	v_fmamk_f32 v78, v78, 0x3e0293ee, v97
	v_exp_f32_e32 v102, v77
	v_add_f32_e32 v64, v92, v64
	v_fmac_f32_e32 v97, 0x3e0293ee, v79
	v_exp_f32_e32 v103, v78
	v_add_f32_e32 v64, v93, v64
	v_exp_f32_e32 v97, v97
	v_add_f32_e32 v64, v94, v64
	v_add_f32_e32 v64, v95, v64
	v_add_f32_e32 v64, v102, v64
	v_add_f32_e32 v64, v103, v64
	v_add_f32_e32 v64, v97, v64
	v_mov_b32_e32 v65, v64
	s_nop 1
	v_permlane32_swap_b32_e32 v64, v65
	v_cvt_pk_bf16_f32 v78, v82, v84
	v_cvt_pk_bf16_f32 v79, v80, v83
	v_cvt_pk_bf16_f32 v80, v75, v81
	v_cvt_pk_bf16_f32 v81, v74, v76
	v_cvt_pk_bf16_f32 v74, v71, v73
	v_cvt_pk_bf16_f32 v75, v69, v72
	v_cvt_pk_bf16_f32 v76, v67, v70
	v_cvt_pk_bf16_f32 v77, v66, v68
	v_cvt_pk_bf16_f32 v66, v98, v99
	v_cvt_pk_bf16_f32 v67, v85, v86
	v_cvt_pk_bf16_f32 v68, v87, v88
	v_cvt_pk_bf16_f32 v69, v89, v90
	v_cvt_pk_bf16_f32 v70, v91, v92
	v_cvt_pk_bf16_f32 v71, v93, v94
	v_cvt_pk_bf16_f32 v72, v95, v102
	v_cvt_pk_bf16_f32 v73, v103, v97
	s_nop 0
	v_permlane32_swap_b32_e32 v78, v80
	v_permlane32_swap_b32_e32 v79, v81
	v_permlane32_swap_b32_e32 v74, v76
	v_permlane32_swap_b32_e32 v75, v77
	v_permlane32_swap_b32_e32 v66, v68
	v_permlane32_swap_b32_e32 v67, v69
	v_permlane32_swap_b32_e32 v70, v72
	v_permlane32_swap_b32_e32 v71, v73
	ds_read_b64_tr_b16 v[82:83], v185 offset:0
	ds_read_b64_tr_b16 v[84:85], v185 offset:0x800
	ds_read_b64_tr_b16 v[86:87], v185 offset:0x1000
	ds_read_b64_tr_b16 v[88:89], v185 offset:0x1800
	ds_read_b64_tr_b16 v[90:91], v185 offset:0x2000
	ds_read_b64_tr_b16 v[92:93], v185 offset:0x2800
	ds_read_b64_tr_b16 v[102:103], v185 offset:0x3000
	ds_read_b64_tr_b16 v[104:105], v185 offset:0x3800
	s_waitcnt lgkmcnt(0)
	s_nop 0
	v_mfma_f32_32x32x16_bf16 v[0:15], v[82:85], v[78:81], v[0:15]
	ds_read_b64_tr_b16 v[82:83], v185 offset:0x200
	ds_read_b64_tr_b16 v[84:85], v185 offset:0xa00
	v_mfma_f32_32x32x16_bf16 v[0:15], v[86:89], v[74:77], v[0:15]
	ds_read_b64_tr_b16 v[86:87], v185 offset:0x1200
	ds_read_b64_tr_b16 v[88:89], v185 offset:0x1a00
	v_mfma_f32_32x32x16_bf16 v[0:15], v[90:93], v[66:69], v[0:15]
	ds_read_b64_tr_b16 v[90:91], v185 offset:0x2200
	ds_read_b64_tr_b16 v[92:93], v185 offset:0x2a00
	v_mfma_f32_32x32x16_bf16 v[0:15], v[102:105], v[70:73], v[0:15]
	ds_read_b64_tr_b16 v[102:103], v185 offset:0x3200
	ds_read_b64_tr_b16 v[104:105], v185 offset:0x3a00
	s_waitcnt lgkmcnt(0)
	v_mfma_f32_32x32x16_bf16 v[48:63], v[82:85], v[78:81], v[48:63]
	ds_read_b64_tr_b16 v[82:83], v185 offset:0x400
	ds_read_b64_tr_b16 v[84:85], v185 offset:0xc00
	v_mfma_f32_32x32x16_bf16 v[48:63], v[86:89], v[74:77], v[48:63]
	ds_read_b64_tr_b16 v[86:87], v185 offset:0x1400
	ds_read_b64_tr_b16 v[88:89], v185 offset:0x1c00
	v_mfma_f32_32x32x16_bf16 v[48:63], v[90:93], v[66:69], v[48:63]
	ds_read_b64_tr_b16 v[90:91], v185 offset:0x2400
	ds_read_b64_tr_b16 v[92:93], v185 offset:0x2c00
	v_mfma_f32_32x32x16_bf16 v[48:63], v[102:105], v[70:73], v[48:63]
	ds_read_b64_tr_b16 v[102:103], v185 offset:0x3400
	ds_read_b64_tr_b16 v[104:105], v185 offset:0x3c00
	s_waitcnt lgkmcnt(0)
	v_mfma_f32_32x32x16_bf16 v[32:47], v[82:85], v[78:81], v[32:47]
	ds_read_b64_tr_b16 v[82:83], v185 offset:0x600
	ds_read_b64_tr_b16 v[84:85], v185 offset:0xe00
	v_mfma_f32_32x32x16_bf16 v[32:47], v[86:89], v[74:77], v[32:47]
	ds_read_b64_tr_b16 v[86:87], v185 offset:0x1600
	ds_read_b64_tr_b16 v[88:89], v185 offset:0x1e00
	v_mfma_f32_32x32x16_bf16 v[32:47], v[90:93], v[66:69], v[32:47]
	ds_read_b64_tr_b16 v[90:91], v185 offset:0x2600
	ds_read_b64_tr_b16 v[92:93], v185 offset:0x2e00
	v_mfma_f32_32x32x16_bf16 v[32:47], v[102:105], v[70:73], v[32:47]
	ds_read_b64_tr_b16 v[102:103], v185 offset:0x3600
	ds_read_b64_tr_b16 v[104:105], v185 offset:0x3e00
	s_waitcnt lgkmcnt(0)
	v_mfma_f32_32x32x16_bf16 v[16:31], v[82:85], v[78:81], v[16:31]
	v_mfma_f32_32x32x16_bf16 v[16:31], v[86:89], v[74:77], v[16:31]
	v_mfma_f32_32x32x16_bf16 v[16:31], v[90:93], v[66:69], v[16:31]
	v_mfma_f32_32x32x16_bf16 v[16:31], v[102:105], v[70:73], v[16:31]
	v_add_f32_e32 v66, v100, v101
	v_fmac_f32_e32 v66, v184, v160
	v_add_f32_e32 v64, v64, v65
	v_fmac_f32_e32 v64, v66, v96
	s_branch .LBB0_184
